# phase 0 score-bound scan: 32 elements per round trip (16 dwordx4 loads in flight) instead of one element per round trip
# speedup vs baseline: 1.1440x; 1.0012x over previous
; DI void phase0(KP p, char* lds) {
;     ...
;     if (blockIdx.x == 0 && tid < 4) {
;       const int l = tid >> 1, isb = tid & 1; const int d = isb ? 64 : 96;
;       const float* gq = (isb ? p->gqa_qn : p->mla_qn) + l * d; const float* gk = (isb ? p->gqa_kn : p->mla_kn) + l * d;
;       float mq = 0.f, mk = 0.f;
;       for (int i = 0; i < d; ++i) { mq = fmaxf(mq, fabsf(gq[i])); mk = fmaxf(mk, fabsf(gk[i])); }
;       ((float*)(ws + WS_SBND))[l * 2 + isb] = sqrtf((float)d) * mq * mk * 1.4426950408889634f;
;     }
.LBB0_496:
	global_load_dwordx4 v[34:37], v[6:7], off
	global_load_dwordx4 v[38:41], v[6:7], off offset:16
	global_load_dwordx4 v[42:45], v[6:7], off offset:32
	global_load_dwordx4 v[46:49], v[6:7], off offset:48
	global_load_dwordx4 v[50:53], v[6:7], off offset:64
	global_load_dwordx4 v[54:57], v[6:7], off offset:80
	global_load_dwordx4 v[58:61], v[6:7], off offset:96
	global_load_dwordx4 v[62:65], v[6:7], off offset:112
	global_load_dwordx4 v[128:131], v[8:9], off
	global_load_dwordx4 v[132:135], v[8:9], off offset:16
	global_load_dwordx4 v[136:139], v[8:9], off offset:32
	global_load_dwordx4 v[140:143], v[8:9], off offset:48
	global_load_dwordx4 v[144:147], v[8:9], off offset:64
	global_load_dwordx4 v[148:151], v[8:9], off offset:80
	global_load_dwordx4 v[152:155], v[8:9], off offset:96
	global_load_dwordx4 v[156:159], v[8:9], off offset:112
	v_add_u32_e32 v12, 0xffffffe0, v12
	v_max_f32_e32 v0, v0, v0
	v_max_f32_e32 v11, v11, v11
	v_cmp_eq_u32_e32 vcc, 0, v12
	v_lshl_add_u64 v[8:9], v[8:9], 0, 64
	v_lshl_add_u64 v[6:7], v[6:7], 0, 64
	v_lshl_add_u64 v[8:9], v[8:9], 0, 64
	v_lshl_add_u64 v[6:7], v[6:7], 0, 64
	s_or_b64 s[18:19], vcc, s[18:19]
	s_waitcnt vmcnt(0)
	v_max_f32_e64 v34, |v34|, |v34|
	v_max_f32_e64 v128, |v128|, |v128|
	v_max_f32_e32 v0, v0, v34
	v_max_f32_e32 v11, v11, v128
	v_max_f32_e64 v35, |v35|, |v35|
	v_max_f32_e64 v129, |v129|, |v129|
	v_max_f32_e32 v0, v0, v35
	v_max_f32_e32 v11, v11, v129
	v_max_f32_e64 v36, |v36|, |v36|
	v_max_f32_e64 v130, |v130|, |v130|
	v_max_f32_e32 v0, v0, v36
	v_max_f32_e32 v11, v11, v130
	v_max_f32_e64 v37, |v37|, |v37|
	v_max_f32_e64 v131, |v131|, |v131|
	v_max_f32_e32 v0, v0, v37
	v_max_f32_e32 v11, v11, v131
	v_max_f32_e64 v38, |v38|, |v38|
	v_max_f32_e64 v132, |v132|, |v132|
	v_max_f32_e32 v0, v0, v38
	v_max_f32_e32 v11, v11, v132
	v_max_f32_e64 v39, |v39|, |v39|
	v_max_f32_e64 v133, |v133|, |v133|
	v_max_f32_e32 v0, v0, v39
	v_max_f32_e32 v11, v11, v133
	v_max_f32_e64 v40, |v40|, |v40|
	v_max_f32_e64 v134, |v134|, |v134|
	v_max_f32_e32 v0, v0, v40
	v_max_f32_e32 v11, v11, v134
	v_max_f32_e64 v41, |v41|, |v41|
	v_max_f32_e64 v135, |v135|, |v135|
	v_max_f32_e32 v0, v0, v41
	v_max_f32_e32 v11, v11, v135
	v_max_f32_e64 v42, |v42|, |v42|
	v_max_f32_e64 v136, |v136|, |v136|
	v_max_f32_e32 v0, v0, v42
	v_max_f32_e32 v11, v11, v136
	v_max_f32_e64 v43, |v43|, |v43|
	v_max_f32_e64 v137, |v137|, |v137|
	v_max_f32_e32 v0, v0, v43
	v_max_f32_e32 v11, v11, v137
	v_max_f32_e64 v44, |v44|, |v44|
	v_max_f32_e64 v138, |v138|, |v138|
	v_max_f32_e32 v0, v0, v44
	v_max_f32_e32 v11, v11, v138
	v_max_f32_e64 v45, |v45|, |v45|
	v_max_f32_e64 v139, |v139|, |v139|
	v_max_f32_e32 v0, v0, v45
	v_max_f32_e32 v11, v11, v139
	v_max_f32_e64 v46, |v46|, |v46|
	v_max_f32_e64 v140, |v140|, |v140|
	v_max_f32_e32 v0, v0, v46
	v_max_f32_e32 v11, v11, v140
	v_max_f32_e64 v47, |v47|, |v47|
	v_max_f32_e64 v141, |v141|, |v141|
	v_max_f32_e32 v0, v0, v47
	v_max_f32_e32 v11, v11, v141
	v_max_f32_e64 v48, |v48|, |v48|
	v_max_f32_e64 v142, |v142|, |v142|
	v_max_f32_e32 v0, v0, v48
	v_max_f32_e32 v11, v11, v142
	v_max_f32_e64 v49, |v49|, |v49|
	v_max_f32_e64 v143, |v143|, |v143|
	v_max_f32_e32 v0, v0, v49
	v_max_f32_e32 v11, v11, v143
	v_max_f32_e64 v50, |v50|, |v50|
	v_max_f32_e64 v144, |v144|, |v144|
	v_max_f32_e32 v0, v0, v50
	v_max_f32_e32 v11, v11, v144
	v_max_f32_e64 v51, |v51|, |v51|
	v_max_f32_e64 v145, |v145|, |v145|
	v_max_f32_e32 v0, v0, v51
	v_max_f32_e32 v11, v11, v145
	v_max_f32_e64 v52, |v52|, |v52|
	v_max_f32_e64 v146, |v146|, |v146|
	v_max_f32_e32 v0, v0, v52
	v_max_f32_e32 v11, v11, v146
	v_max_f32_e64 v53, |v53|, |v53|
	v_max_f32_e64 v147, |v147|, |v147|
	v_max_f32_e32 v0, v0, v53
	v_max_f32_e32 v11, v11, v147
	v_max_f32_e64 v54, |v54|, |v54|
	v_max_f32_e64 v148, |v148|, |v148|
	v_max_f32_e32 v0, v0, v54
	v_max_f32_e32 v11, v11, v148
	v_max_f32_e64 v55, |v55|, |v55|
	v_max_f32_e64 v149, |v149|, |v149|
	v_max_f32_e32 v0, v0, v55
	v_max_f32_e32 v11, v11, v149
	v_max_f32_e64 v56, |v56|, |v56|
	v_max_f32_e64 v150, |v150|, |v150|
	v_max_f32_e32 v0, v0, v56
	v_max_f32_e32 v11, v11, v150
	v_max_f32_e64 v57, |v57|, |v57|
	v_max_f32_e64 v151, |v151|, |v151|
	v_max_f32_e32 v0, v0, v57
	v_max_f32_e32 v11, v11, v151
	v_max_f32_e64 v58, |v58|, |v58|
	v_max_f32_e64 v152, |v152|, |v152|
	v_max_f32_e32 v0, v0, v58
	v_max_f32_e32 v11, v11, v152
	v_max_f32_e64 v59, |v59|, |v59|
	v_max_f32_e64 v153, |v153|, |v153|
	v_max_f32_e32 v0, v0, v59
	v_max_f32_e32 v11, v11, v153
	v_max_f32_e64 v60, |v60|, |v60|
	v_max_f32_e64 v154, |v154|, |v154|
	v_max_f32_e32 v0, v0, v60
	v_max_f32_e32 v11, v11, v154
	v_max_f32_e64 v61, |v61|, |v61|
	v_max_f32_e64 v155, |v155|, |v155|
	v_max_f32_e32 v0, v0, v61
	v_max_f32_e32 v11, v11, v155
	v_max_f32_e64 v62, |v62|, |v62|
	v_max_f32_e64 v156, |v156|, |v156|
	v_max_f32_e32 v0, v0, v62
	v_max_f32_e32 v11, v11, v156
	v_max_f32_e64 v63, |v63|, |v63|
	v_max_f32_e64 v157, |v157|, |v157|
	v_max_f32_e32 v0, v0, v63
	v_max_f32_e32 v11, v11, v157
	v_max_f32_e64 v64, |v64|, |v64|
	v_max_f32_e64 v158, |v158|, |v158|
	v_max_f32_e32 v0, v0, v64
	v_max_f32_e32 v11, v11, v158
	v_max_f32_e64 v65, |v65|, |v65|
	v_max_f32_e64 v159, |v159|, |v159|
	v_max_f32_e32 v0, v0, v65
	v_max_f32_e32 v11, v11, v159
	s_andn2_b64 exec, exec, s[18:19]
	s_cbranch_execnz .LBB0_496
	s_or_b64 exec, exec, s[18:19]
	v_cvt_f32_ubyte0_e32 v6, v10
	s_mov_b32 s2, 0xf800000
	v_mul_f32_e32 v7, 0x4f800000, v6
	v_cmp_gt_f32_e32 vcc, s2, v6
	s_nop 1
	v_cndmask_b32_e32 v6, v6, v7, vcc
	v_sqrt_f32_e32 v7, v6
	s_nop 0
	v_add_u32_e32 v8, -1, v7
	v_fma_f32 v10, -v8, v7, v6
	v_add_u32_e32 v9, 1, v7
	v_cmp_ge_f32_e64 s[40:41], 0, v10
	s_nop 1
	v_cndmask_b32_e64 v8, v7, v8, s[40:41]
	v_fma_f32 v7, -v9, v7, v6
	v_cmp_lt_f32_e64 s[40:41], 0, v7
	s_nop 1
	v_cndmask_b32_e64 v7, v8, v9, s[40:41]
	v_mul_f32_e32 v8, 0x37800000, v7
	v_cndmask_b32_e32 v7, v7, v8, vcc
	v_mov_b32_e32 v8, 0x260
	v_cmp_class_f32_e32 vcc, v6, v8
	s_nop 1
	v_cndmask_b32_e32 v6, v7, v6, vcc
	v_mul_f32_e32 v0, v6, v0
	v_lshl_add_u64 v[6:7], v[2:3], 2, s[36:37]
	v_mul_f32_e32 v0, v11, v0
	v_add_co_u32_e32 v6, vcc, 0x69000, v6
	v_mul_f32_e32 v0, 0x3fb8aa3b, v0
	s_nop 0
	v_addc_co_u32_e32 v7, vcc, 0, v7, vcc
	global_store_dword v[6:7], v0, off
